# next-head u rows requested progressively (row m-1 right after dot product m) instead of all eight after the last dot product
# baseline (speedup 1.0000x reference)
.LBB0_330:
	v_add_u32_e32 v254, s24, v239
	ds_read_b32 v250, v254 offset:512
	s_waitcnt vmcnt(22)
	v_cvt_scalef32_pk32_f32_fp6 v[0:31], v[32:37], 1.0
	v_pk_fma_f32 v[0:1], v[0:1], v[152:153], 0 op_sel_hi:[1,1,0]
	v_pk_fma_f32 v[2:3], v[2:3], v[170:171], 0 op_sel_hi:[1,1,0]
	v_pk_fma_f32 v[0:1], v[4:5], v[148:149], v[0:1]
	v_pk_fma_f32 v[2:3], v[6:7], v[172:173], v[2:3]
	v_pk_fma_f32 v[0:1], v[8:9], v[144:145], v[0:1]
	v_pk_fma_f32 v[2:3], v[10:11], v[174:175], v[2:3]
	v_pk_fma_f32 v[0:1], v[12:13], v[140:141], v[0:1]
	v_pk_fma_f32 v[2:3], v[14:15], v[178:179], v[2:3]
	v_pk_fma_f32 v[0:1], v[16:17], v[168:169], v[0:1]
	v_pk_fma_f32 v[2:3], v[18:19], v[180:181], v[2:3]
	v_pk_fma_f32 v[0:1], v[20:21], v[164:165], v[0:1]
	v_pk_fma_f32 v[2:3], v[22:23], v[182:183], v[2:3]
	v_pk_fma_f32 v[0:1], v[24:25], v[160:161], v[0:1]
	v_pk_fma_f32 v[2:3], v[26:27], v[184:185], v[2:3]
	v_pk_fma_f32 v[0:1], v[28:29], v[156:157], v[0:1]
	v_pk_fma_f32 v[2:3], v[30:31], v[186:187], v[2:3]
	v_add_f32_e32 v4, v2, v3
	v_add_f32_e32 v5, v0, v1
	v_add_f32_e32 v117, v4, v5
	s_waitcnt lgkmcnt(0)
	ds_bpermute_b32 v251, v255, v250
	s_waitcnt vmcnt(20)
	v_cvt_scalef32_pk32_f32_fp6 v[0:31], v[38:43], 1.0
	v_pk_fma_f32 v[0:1], v[0:1], v[152:153], 0 op_sel_hi:[1,1,0]
	v_pk_fma_f32 v[2:3], v[2:3], v[170:171], 0 op_sel_hi:[1,1,0]
	v_pk_fma_f32 v[0:1], v[4:5], v[148:149], v[0:1]
	v_pk_fma_f32 v[2:3], v[6:7], v[172:173], v[2:3]
	v_pk_fma_f32 v[0:1], v[8:9], v[144:145], v[0:1]
	v_pk_fma_f32 v[2:3], v[10:11], v[174:175], v[2:3]
	v_pk_fma_f32 v[0:1], v[12:13], v[140:141], v[0:1]
	v_pk_fma_f32 v[2:3], v[14:15], v[178:179], v[2:3]
	v_pk_fma_f32 v[0:1], v[16:17], v[168:169], v[0:1]
	v_pk_fma_f32 v[2:3], v[18:19], v[180:181], v[2:3]
	v_pk_fma_f32 v[0:1], v[20:21], v[164:165], v[0:1]
	v_pk_fma_f32 v[2:3], v[22:23], v[182:183], v[2:3]
	v_pk_fma_f32 v[0:1], v[24:25], v[160:161], v[0:1]
	v_pk_fma_f32 v[2:3], v[26:27], v[184:185], v[2:3]
	v_pk_fma_f32 v[0:1], v[28:29], v[156:157], v[0:1]
	v_pk_fma_f32 v[2:3], v[30:31], v[186:187], v[2:3]
	v_add_f32_e32 v4, v2, v3
	v_add_f32_e32 v5, v0, v1
	v_add_f32_e32 v131, v4, v5
	s_waitcnt lgkmcnt(0)
	v_mad_i64_i32 v[22:23], s[2:3], v251, s28, v[118:119]
	global_load_dwordx2 v[36:37], v[22:23], off offset:16
	global_load_dwordx4 v[32:35], v[22:23], off
	v_add_u32_e32 v254, 16, v255
	ds_bpermute_b32 v253, v254, v250
	s_waitcnt vmcnt(20)
	v_cvt_scalef32_pk32_f32_fp6 v[0:31], v[44:49], 1.0
	v_pk_fma_f32 v[0:1], v[0:1], v[152:153], 0 op_sel_hi:[1,1,0]
	v_pk_fma_f32 v[2:3], v[2:3], v[170:171], 0 op_sel_hi:[1,1,0]
	v_pk_fma_f32 v[0:1], v[4:5], v[148:149], v[0:1]
	v_pk_fma_f32 v[2:3], v[6:7], v[172:173], v[2:3]
	v_pk_fma_f32 v[0:1], v[8:9], v[144:145], v[0:1]
	v_pk_fma_f32 v[2:3], v[10:11], v[174:175], v[2:3]
	v_pk_fma_f32 v[0:1], v[12:13], v[140:141], v[0:1]
	v_pk_fma_f32 v[2:3], v[14:15], v[178:179], v[2:3]
	v_pk_fma_f32 v[0:1], v[16:17], v[168:169], v[0:1]
	v_pk_fma_f32 v[2:3], v[18:19], v[180:181], v[2:3]
	v_pk_fma_f32 v[0:1], v[20:21], v[164:165], v[0:1]
	v_pk_fma_f32 v[2:3], v[22:23], v[182:183], v[2:3]
	v_pk_fma_f32 v[0:1], v[24:25], v[160:161], v[0:1]
	v_pk_fma_f32 v[2:3], v[26:27], v[184:185], v[2:3]
	v_pk_fma_f32 v[0:1], v[28:29], v[156:157], v[0:1]
	v_pk_fma_f32 v[2:3], v[30:31], v[186:187], v[2:3]
	v_add_f32_e32 v4, v2, v3
	v_add_f32_e32 v5, v0, v1
	v_add_f32_e32 v133, v4, v5
	s_waitcnt lgkmcnt(0)
	v_mad_i64_i32 v[22:23], s[2:3], v253, s28, v[118:119]
	global_load_dwordx2 v[42:43], v[22:23], off offset:16
	global_load_dwordx4 v[38:41], v[22:23], off
	v_add_u32_e32 v254, 32, v255
	ds_bpermute_b32 v251, v254, v250
	s_waitcnt vmcnt(20)
	v_cvt_scalef32_pk32_f32_fp6 v[0:31], v[50:55], 1.0
	v_pk_fma_f32 v[0:1], v[0:1], v[152:153], 0 op_sel_hi:[1,1,0]
	v_pk_fma_f32 v[2:3], v[2:3], v[170:171], 0 op_sel_hi:[1,1,0]
	v_pk_fma_f32 v[0:1], v[4:5], v[148:149], v[0:1]
	v_pk_fma_f32 v[2:3], v[6:7], v[172:173], v[2:3]
	v_pk_fma_f32 v[0:1], v[8:9], v[144:145], v[0:1]
	v_pk_fma_f32 v[2:3], v[10:11], v[174:175], v[2:3]
	v_pk_fma_f32 v[0:1], v[12:13], v[140:141], v[0:1]
	v_pk_fma_f32 v[2:3], v[14:15], v[178:179], v[2:3]
	v_pk_fma_f32 v[0:1], v[16:17], v[168:169], v[0:1]
	v_pk_fma_f32 v[2:3], v[18:19], v[180:181], v[2:3]
	v_pk_fma_f32 v[0:1], v[20:21], v[164:165], v[0:1]
	v_pk_fma_f32 v[2:3], v[22:23], v[182:183], v[2:3]
	v_pk_fma_f32 v[0:1], v[24:25], v[160:161], v[0:1]
	v_pk_fma_f32 v[2:3], v[26:27], v[184:185], v[2:3]
	v_pk_fma_f32 v[0:1], v[28:29], v[156:157], v[0:1]
	v_pk_fma_f32 v[2:3], v[30:31], v[186:187], v[2:3]
	v_add_f32_e32 v4, v2, v3
	v_add_f32_e32 v5, v0, v1
	v_add_f32_e32 v218, v4, v5
	s_waitcnt lgkmcnt(0)
	v_mad_i64_i32 v[22:23], s[2:3], v251, s28, v[118:119]
	global_load_dwordx2 v[48:49], v[22:23], off offset:16
	global_load_dwordx4 v[44:47], v[22:23], off
	v_add_u32_e32 v254, 48, v255
	ds_bpermute_b32 v253, v254, v250
	s_waitcnt vmcnt(20)
	v_cvt_scalef32_pk32_f32_fp6 v[0:31], v[56:61], 1.0
	v_pk_fma_f32 v[0:1], v[0:1], v[152:153], 0 op_sel_hi:[1,1,0]
	v_pk_fma_f32 v[2:3], v[2:3], v[170:171], 0 op_sel_hi:[1,1,0]
	v_pk_fma_f32 v[0:1], v[4:5], v[148:149], v[0:1]
	v_pk_fma_f32 v[2:3], v[6:7], v[172:173], v[2:3]
	v_pk_fma_f32 v[0:1], v[8:9], v[144:145], v[0:1]
	v_pk_fma_f32 v[2:3], v[10:11], v[174:175], v[2:3]
	v_pk_fma_f32 v[0:1], v[12:13], v[140:141], v[0:1]
	v_pk_fma_f32 v[2:3], v[14:15], v[178:179], v[2:3]
	v_pk_fma_f32 v[0:1], v[16:17], v[168:169], v[0:1]
	v_pk_fma_f32 v[2:3], v[18:19], v[180:181], v[2:3]
	v_pk_fma_f32 v[0:1], v[20:21], v[164:165], v[0:1]
	v_pk_fma_f32 v[2:3], v[22:23], v[182:183], v[2:3]
	v_pk_fma_f32 v[0:1], v[24:25], v[160:161], v[0:1]
	v_pk_fma_f32 v[2:3], v[26:27], v[184:185], v[2:3]
	v_pk_fma_f32 v[0:1], v[28:29], v[156:157], v[0:1]
	v_pk_fma_f32 v[2:3], v[30:31], v[186:187], v[2:3]
	v_add_f32_e32 v4, v2, v3
	v_add_f32_e32 v5, v0, v1
	v_add_f32_e32 v219, v4, v5
	s_waitcnt lgkmcnt(0)
	v_mad_i64_i32 v[22:23], s[2:3], v253, s28, v[118:119]
	global_load_dwordx2 v[54:55], v[22:23], off offset:16
	global_load_dwordx4 v[50:53], v[22:23], off
	v_add_u32_e32 v254, 64, v255
	ds_bpermute_b32 v251, v254, v250
	s_waitcnt vmcnt(20)
	v_cvt_scalef32_pk32_f32_fp6 v[0:31], v[62:67], 1.0
	v_pk_fma_f32 v[0:1], v[0:1], v[152:153], 0 op_sel_hi:[1,1,0]
	v_pk_fma_f32 v[2:3], v[2:3], v[170:171], 0 op_sel_hi:[1,1,0]
	v_pk_fma_f32 v[0:1], v[4:5], v[148:149], v[0:1]
	v_pk_fma_f32 v[2:3], v[6:7], v[172:173], v[2:3]
	v_pk_fma_f32 v[0:1], v[8:9], v[144:145], v[0:1]
	v_pk_fma_f32 v[2:3], v[10:11], v[174:175], v[2:3]
	v_pk_fma_f32 v[0:1], v[12:13], v[140:141], v[0:1]
	v_pk_fma_f32 v[2:3], v[14:15], v[178:179], v[2:3]
	v_pk_fma_f32 v[0:1], v[16:17], v[168:169], v[0:1]
	v_pk_fma_f32 v[2:3], v[18:19], v[180:181], v[2:3]
	v_pk_fma_f32 v[0:1], v[20:21], v[164:165], v[0:1]
	v_pk_fma_f32 v[2:3], v[22:23], v[182:183], v[2:3]
	v_pk_fma_f32 v[0:1], v[24:25], v[160:161], v[0:1]
	v_pk_fma_f32 v[2:3], v[26:27], v[184:185], v[2:3]
	v_pk_fma_f32 v[0:1], v[28:29], v[156:157], v[0:1]
	v_pk_fma_f32 v[2:3], v[30:31], v[186:187], v[2:3]
	v_add_f32_e32 v4, v2, v3
	v_add_f32_e32 v5, v0, v1
	v_add_f32_e32 v246, v4, v5
	s_waitcnt lgkmcnt(0)
	v_mad_i64_i32 v[22:23], s[2:3], v251, s28, v[118:119]
	global_load_dwordx2 v[60:61], v[22:23], off offset:16
	global_load_dwordx4 v[56:59], v[22:23], off
	v_add_u32_e32 v254, 80, v255
	ds_bpermute_b32 v253, v254, v250
	s_waitcnt vmcnt(20)
	v_cvt_scalef32_pk32_f32_fp6 v[0:31], v[68:73], 1.0
	v_pk_fma_f32 v[0:1], v[0:1], v[152:153], 0 op_sel_hi:[1,1,0]
	v_pk_fma_f32 v[2:3], v[2:3], v[170:171], 0 op_sel_hi:[1,1,0]
	v_pk_fma_f32 v[0:1], v[4:5], v[148:149], v[0:1]
	v_pk_fma_f32 v[2:3], v[6:7], v[172:173], v[2:3]
	v_pk_fma_f32 v[0:1], v[8:9], v[144:145], v[0:1]
	v_pk_fma_f32 v[2:3], v[10:11], v[174:175], v[2:3]
	v_pk_fma_f32 v[0:1], v[12:13], v[140:141], v[0:1]
	v_pk_fma_f32 v[2:3], v[14:15], v[178:179], v[2:3]
	v_pk_fma_f32 v[0:1], v[16:17], v[168:169], v[0:1]
	v_pk_fma_f32 v[2:3], v[18:19], v[180:181], v[2:3]
	v_pk_fma_f32 v[0:1], v[20:21], v[164:165], v[0:1]
	v_pk_fma_f32 v[2:3], v[22:23], v[182:183], v[2:3]
	v_pk_fma_f32 v[0:1], v[24:25], v[160:161], v[0:1]
	v_pk_fma_f32 v[2:3], v[26:27], v[184:185], v[2:3]
	v_pk_fma_f32 v[0:1], v[28:29], v[156:157], v[0:1]
	v_pk_fma_f32 v[2:3], v[30:31], v[186:187], v[2:3]
	v_add_f32_e32 v4, v2, v3
	v_add_f32_e32 v5, v0, v1
	v_add_f32_e32 v247, v4, v5
	s_waitcnt lgkmcnt(0)
	v_mad_i64_i32 v[22:23], s[2:3], v253, s28, v[118:119]
	global_load_dwordx2 v[66:67], v[22:23], off offset:16
	global_load_dwordx4 v[62:65], v[22:23], off
	v_add_u32_e32 v254, 96, v255
	ds_bpermute_b32 v251, v254, v250
	s_waitcnt vmcnt(20)
	v_cvt_scalef32_pk32_f32_fp6 v[0:31], v[74:79], 1.0
	v_pk_fma_f32 v[0:1], v[0:1], v[152:153], 0 op_sel_hi:[1,1,0]
	v_pk_fma_f32 v[2:3], v[2:3], v[170:171], 0 op_sel_hi:[1,1,0]
	v_pk_fma_f32 v[0:1], v[4:5], v[148:149], v[0:1]
	v_pk_fma_f32 v[2:3], v[6:7], v[172:173], v[2:3]
	v_pk_fma_f32 v[0:1], v[8:9], v[144:145], v[0:1]
	v_pk_fma_f32 v[2:3], v[10:11], v[174:175], v[2:3]
	v_pk_fma_f32 v[0:1], v[12:13], v[140:141], v[0:1]
	v_pk_fma_f32 v[2:3], v[14:15], v[178:179], v[2:3]
	v_pk_fma_f32 v[0:1], v[16:17], v[168:169], v[0:1]
	v_pk_fma_f32 v[2:3], v[18:19], v[180:181], v[2:3]
	v_pk_fma_f32 v[0:1], v[20:21], v[164:165], v[0:1]
	v_pk_fma_f32 v[2:3], v[22:23], v[182:183], v[2:3]
	v_pk_fma_f32 v[0:1], v[24:25], v[160:161], v[0:1]
	v_pk_fma_f32 v[2:3], v[26:27], v[184:185], v[2:3]
	v_pk_fma_f32 v[0:1], v[28:29], v[156:157], v[0:1]
	v_pk_fma_f32 v[2:3], v[30:31], v[186:187], v[2:3]
	v_add_f32_e32 v4, v2, v3
	v_add_f32_e32 v5, v0, v1
	v_add_f32_e32 v1, v4, v5
	s_waitcnt lgkmcnt(0)
	v_mad_i64_i32 v[22:23], s[2:3], v251, s28, v[118:119]
	global_load_dwordx2 v[72:73], v[22:23], off offset:16
	global_load_dwordx4 v[68:71], v[22:23], off
	v_add_u32_e32 v254, 112, v255
	ds_bpermute_b32 v253, v254, v250
	s_waitcnt lgkmcnt(0)
	v_mad_i64_i32 v[22:23], s[2:3], v253, s28, v[118:119]
	global_load_dwordx2 v[78:79], v[22:23], off offset:16
	global_load_dwordx4 v[74:77], v[22:23], off
	v_add_u32_e32 v8, s24, v239
	v_add_u32_e32 v13, 0, v255
	v_add_u32_e32 v15, 16, v255
	v_add_u32_e32 v18, 32, v255
	v_add_u32_e32 v19, 48, v255
	v_add_u32_e32 v20, 64, v255
	v_add_u32_e32 v21, 80, v255
	v_add_u32_e32 v26, 96, v255
	v_add_u32_e32 v27, 112, v255
	ds_bpermute_b32 v0, v13, v250
	ds_bpermute_b32 v2, v15, v250
	ds_bpermute_b32 v3, v18, v250
	ds_bpermute_b32 v6, v19, v250
	ds_bpermute_b32 v7, v20, v250
	ds_bpermute_b32 v10, v21, v250
	ds_bpermute_b32 v11, v26, v250
	ds_bpermute_b32 v14, v27, v250
	s_waitcnt lgkmcnt(0)
	ds_read_b64 v[16:17], v8
	v_cndmask_b32_e64 v4, v117, v219, s[14:15]
	ds_bpermute_b32 v4, v242, v4
	v_cndmask_b32_e64 v5, v219, v117, s[14:15]
	v_cndmask_b32_e64 v8, v131, v246, s[14:15]
	ds_bpermute_b32 v8, v242, v8
	v_cndmask_b32_e64 v12, v218, v1, s[14:15]
	s_waitcnt lgkmcnt(1)
	v_add_f32_e32 v4, v5, v4
	v_cndmask_b32_e64 v5, v133, v247, s[14:15]
	ds_bpermute_b32 v5, v242, v5
	ds_bpermute_b32 v12, v242, v12
	v_cndmask_b32_e64 v9, v246, v131, s[14:15]
	s_waitcnt lgkmcnt(2)
	v_add_f32_e32 v8, v9, v8
	v_cndmask_b32_e64 v9, v247, v133, s[14:15]
	v_cndmask_b32_e64 v1, v1, v218, s[14:15]
	s_waitcnt lgkmcnt(1)
	v_add_f32_e32 v5, v9, v5
	s_waitcnt lgkmcnt(0)
	v_add_f32_e32 v1, v1, v12
	v_cndmask_b32_e64 v9, v4, v5, s[16:17]
	v_cndmask_b32_e64 v12, v8, v1, s[16:17]
	ds_bpermute_b32 v9, v241, v9
	ds_bpermute_b32 v12, v241, v12
	v_cndmask_b32_e64 v4, v5, v4, s[16:17]
	v_cndmask_b32_e64 v1, v1, v8, s[16:17]
	s_waitcnt lgkmcnt(1)
	v_add_f32_e32 v4, v4, v9
	s_waitcnt lgkmcnt(0)
	v_add_f32_e32 v1, v1, v12
	v_cndmask_b32_e64 v5, v4, v1, s[18:19]
	ds_bpermute_b32 v5, v240, v5
	v_cndmask_b32_e64 v1, v1, v4, s[18:19]
	s_waitcnt lgkmcnt(0)
	v_add_f32_e32 v1, v1, v5
	ds_bpermute_b32 v4, v244, v1
	s_waitcnt lgkmcnt(0)
	v_add_f32_e32 v1, v1, v4
	ds_bpermute_b32 v4, v245, v1
	s_waitcnt lgkmcnt(0)
	v_add_f32_e32 v1, v1, v4
	v_mul_f32_e32 v18, 0x3caaaaab, v1
	v_mul_f32_e32 v16, 0x3f3504f3, v18
	v_cmp_nlt_f32_e64 s[2:3], |v16|, 1.0
	s_and_saveexec_b64 s[26:27], s[2:3]
	s_xor_b64 s[2:3], exec, s[26:27]
	s_cbranch_execz .LBB0_332
	s_mov_b32 s25, 0x378e98ab
	v_fma_f32 v1, |v16|, s25, v233
	s_mov_b32 s25, 0x3b7cd369
	v_fma_f32 v1, |v16|, v1, s25
	s_mov_b32 s25, 0xbcc618b2
	v_fma_f32 v1, |v16|, v1, s25
	s_mov_b32 s25, 0x3dda74e4
	v_fma_f32 v1, |v16|, v1, s25
	s_mov_b32 s25, 0x3f228afd
	v_fma_f32 v1, |v16|, v1, s25
	s_mov_b32 s25, 0x3e03c728
	v_fma_f32 v1, |v16|, v1, s25
	v_fma_f32 v1, |v16|, v1, |v16|
	v_mul_f32_e32 v4, 0xbfb8aa3b, v1
	s_mov_b32 s25, 0xbfb8aa3b
	v_fma_f32 v5, v1, s25, -v4
	v_rndne_f32_e32 v8, v4
	v_fmac_f32_e32 v5, 0xb2a5705f, v1
	v_sub_f32_e32 v4, v4, v8
	v_add_f32_e32 v4, v4, v5
	v_cvt_i32_f32_e32 v5, v8
	v_exp_f32_e32 v4, v4
	s_mov_b32 s25, 0x42ce8ed0
	v_cmp_nlt_f32_e32 vcc, s25, v1
	s_mov_b32 s25, 0xc2b17218
	v_ldexp_f32 v4, v4, v5
	v_cndmask_b32_e32 v4, 0, v4, vcc
	v_cmp_ngt_f32_e32 vcc, s25, v1
	s_nop 1
	v_cndmask_b32_e32 v1, v234, v4, vcc
	v_sub_f32_e32 v19, 1.0, v1
